# GEMM epilogues de-serialised: down-proj residual loads batched 4 per row group (one wait), SwiGLU per-row sums of squares loaded up front (was load+vmcnt(0) per step)
# speedup vs baseline: 1.0582x; 1.0019x over previous
.LBB0_547:
	v_lshl_add_u32 v144, s36, 8, v152
	v_ashrrev_i32_e32 v145, 31, v144
	v_lshl_add_u64 v[150:151], v[144:145], 2, s[10:11]
	global_load_dword v244, v[150:151], off
	global_load_dword v245, v[150:151], off offset:64
	global_load_dword v246, v[150:151], off offset:128
	global_load_dword v247, v[150:151], off offset:192
	global_load_dword v248, v[150:151], off offset:512
	global_load_dword v249, v[150:151], off offset:576
	global_load_dword v250, v[150:151], off offset:640
	global_load_dword v251, v[150:151], off offset:704
	v_or_b32_e32 v162, 16, v144
	v_ashrrev_i32_e32 v163, 31, v162
	v_lshl_add_u64 v[166:167], v[162:163], 2, s[10:11]
	v_lshl_or_b32 v148, s33, 7, v154
	v_mov_b64_e32 v[146:147], s[12:13]
	v_ashrrev_i32_e32 v149, 31, v148
	v_mad_i64_i32 v[160:161], s[38:39], v144, s58, v[146:147]
	v_lshlrev_b64 v[148:149], 1, v[148:149]
	v_lshl_add_u64 v[160:161], v[160:161], 0, v[148:149]
	s_andn2_b64 vcc, exec, s[4:5]
	s_mov_b64 s[4:5], -1
	s_waitcnt vmcnt(0)
	v_fmamk_f32 v145, v244, 0x3a800000, v158
	v_rsq_f32_e32 v164, v145
	s_nop 0
	v_pk_mul_f32 v[124:125], v[124:125], v[164:165] op_sel_hi:[1,0]
	v_pk_mul_f32 v[126:127], v[126:127], v[164:165] op_sel_hi:[1,0]
	v_pk_mul_f32 v[120:121], v[120:121], v[164:165] op_sel_hi:[1,0]
	v_pk_mul_f32 v[122:123], v[122:123], v[164:165] op_sel_hi:[1,0]
	v_pk_mul_f32 v[116:117], v[116:117], v[164:165] op_sel_hi:[1,0]
	v_pk_mul_f32 v[118:119], v[118:119], v[164:165] op_sel_hi:[1,0]
	v_pk_mul_f32 v[112:113], v[112:113], v[164:165] op_sel_hi:[1,0]
	v_pk_mul_f32 v[114:115], v[114:115], v[164:165] op_sel_hi:[1,0]
	v_mul_f32_e32 v145, 0xbfb8aa3b, v124
	v_mul_f32_e32 v159, 0xbfb8aa3b, v125
	v_mul_f32_e32 v163, 0xbfb8aa3b, v126
	v_mul_f32_e32 v164, 0xbfb8aa3b, v127
	v_mul_f32_e32 v165, 0xbfb8aa3b, v120
	v_mul_f32_e32 v169, 0xbfb8aa3b, v121
	v_mul_f32_e32 v170, 0xbfb8aa3b, v122
	v_mul_f32_e32 v171, 0xbfb8aa3b, v123
	v_exp_f32_e32 v145, v145
	v_exp_f32_e32 v159, v159
	v_exp_f32_e32 v163, v163
	v_exp_f32_e32 v164, v164
	v_exp_f32_e32 v165, v165
	v_exp_f32_e32 v169, v169
	v_exp_f32_e32 v170, v170
	v_exp_f32_e32 v171, v171
	v_add_f32_e32 v145, 1.0, v145
	v_add_f32_e32 v159, 1.0, v159
	v_add_f32_e32 v163, 1.0, v163
	v_add_f32_e32 v172, 1.0, v164
	v_add_f32_e32 v173, 1.0, v165
	v_add_f32_e32 v169, 1.0, v169
	v_add_f32_e32 v174, 1.0, v170
	v_add_f32_e32 v175, 1.0, v171
	v_rcp_f32_e32 v164, v145
	v_rcp_f32_e32 v165, v159
	v_rcp_f32_e32 v170, v163
	v_rcp_f32_e32 v171, v172
	v_rcp_f32_e32 v172, v173
	v_rcp_f32_e32 v173, v169
	v_rcp_f32_e32 v174, v174
	v_rcp_f32_e32 v175, v175
	v_pk_mul_f32 v[124:125], v[124:125], v[164:165]
	v_pk_mul_f32 v[126:127], v[126:127], v[170:171]
	v_pk_mul_f32 v[120:121], v[120:121], v[172:173]
	v_pk_mul_f32 v[122:123], v[122:123], v[174:175]
	v_pk_mul_f32 v[116:117], v[116:117], v[124:125]
	v_pk_mul_f32 v[118:119], v[118:119], v[126:127]
	v_pk_mul_f32 v[120:121], v[112:113], v[120:121]
	v_pk_mul_f32 v[122:123], v[114:115], v[122:123]
	v_cvt_pk_bf16_f32 v112, v116, v117
	v_cvt_pk_bf16_f32 v113, v118, v119
	v_cvt_pk_bf16_f32 v114, v120, v121
	v_cvt_pk_bf16_f32 v115, v122, v123
	global_store_dwordx4 v[160:161], v[112:115], off
	s_nop 0
	s_nop 0
	v_or_b32_e32 v112, 32, v144
	v_mad_i64_i32 v[114:115], s[38:39], v162, s58, v[146:147]
	v_lshl_add_u64 v[114:115], v[114:115], 0, v[148:149]
	v_fmamk_f32 v113, v245, 0x3a800000, v158
	v_rsq_f32_e32 v116, v113
	v_ashrrev_i32_e32 v113, 31, v112
	v_lshl_add_u64 v[118:119], v[112:113], 2, s[10:11]
	v_pk_mul_f32 v[108:109], v[108:109], v[116:117] op_sel_hi:[1,0]
	v_pk_mul_f32 v[110:111], v[110:111], v[116:117] op_sel_hi:[1,0]
	v_pk_mul_f32 v[104:105], v[104:105], v[116:117] op_sel_hi:[1,0]
	v_pk_mul_f32 v[106:107], v[106:107], v[116:117] op_sel_hi:[1,0]
	v_pk_mul_f32 v[100:101], v[100:101], v[116:117] op_sel_hi:[1,0]
	v_pk_mul_f32 v[102:103], v[102:103], v[116:117] op_sel_hi:[1,0]
	v_pk_mul_f32 v[96:97], v[96:97], v[116:117] op_sel_hi:[1,0]
	v_pk_mul_f32 v[98:99], v[98:99], v[116:117] op_sel_hi:[1,0]
	v_mul_f32_e32 v113, 0xbfb8aa3b, v108
	v_mul_f32_e32 v116, 0xbfb8aa3b, v109
	v_mul_f32_e32 v117, 0xbfb8aa3b, v110
	v_mul_f32_e32 v120, 0xbfb8aa3b, v111
	v_mul_f32_e32 v121, 0xbfb8aa3b, v104
	v_mul_f32_e32 v122, 0xbfb8aa3b, v105
	v_mul_f32_e32 v123, 0xbfb8aa3b, v106
	v_mul_f32_e32 v124, 0xbfb8aa3b, v107
	v_exp_f32_e32 v113, v113
	v_exp_f32_e32 v116, v116
	v_exp_f32_e32 v117, v117
	v_exp_f32_e32 v120, v120
	v_exp_f32_e32 v121, v121
	v_exp_f32_e32 v122, v122
	v_exp_f32_e32 v123, v123
	v_exp_f32_e32 v124, v124
	v_add_f32_e32 v113, 1.0, v113
	v_add_f32_e32 v125, 1.0, v116
	v_add_f32_e32 v126, 1.0, v117
	v_add_f32_e32 v127, 1.0, v120
	v_add_f32_e32 v145, 1.0, v121
	v_add_f32_e32 v159, 1.0, v122
	v_add_f32_e32 v160, 1.0, v123
	v_add_f32_e32 v161, 1.0, v124
	v_rcp_f32_e32 v116, v113
	v_rcp_f32_e32 v117, v125
	v_rcp_f32_e32 v120, v126
	v_rcp_f32_e32 v121, v127
	v_rcp_f32_e32 v122, v145
	v_rcp_f32_e32 v123, v159
	v_rcp_f32_e32 v124, v160
	v_rcp_f32_e32 v125, v161
	v_pk_mul_f32 v[108:109], v[108:109], v[116:117]
	v_pk_mul_f32 v[110:111], v[110:111], v[120:121]
	v_pk_mul_f32 v[104:105], v[104:105], v[122:123]
	v_pk_mul_f32 v[106:107], v[106:107], v[124:125]
	v_pk_mul_f32 v[100:101], v[100:101], v[108:109]
	v_pk_mul_f32 v[102:103], v[102:103], v[110:111]
	v_pk_mul_f32 v[104:105], v[96:97], v[104:105]
	v_pk_mul_f32 v[106:107], v[98:99], v[106:107]
	v_cvt_pk_bf16_f32 v96, v100, v101
	v_cvt_pk_bf16_f32 v97, v102, v103
	v_cvt_pk_bf16_f32 v98, v104, v105
	v_cvt_pk_bf16_f32 v99, v106, v107
	global_store_dwordx4 v[114:115], v[96:99], off
	s_nop 0
	s_nop 0
	v_or_b32_e32 v96, 48, v144
	v_mad_i64_i32 v[98:99], s[38:39], v112, s58, v[146:147]
	v_lshl_add_u64 v[98:99], v[98:99], 0, v[148:149]
	v_fmamk_f32 v97, v246, 0x3a800000, v158
	v_rsq_f32_e32 v100, v97
	v_ashrrev_i32_e32 v97, 31, v96
	v_lshl_add_u64 v[102:103], v[96:97], 2, s[10:11]
	v_pk_mul_f32 v[92:93], v[92:93], v[100:101] op_sel_hi:[1,0]
	v_pk_mul_f32 v[94:95], v[94:95], v[100:101] op_sel_hi:[1,0]
	v_pk_mul_f32 v[88:89], v[88:89], v[100:101] op_sel_hi:[1,0]
	v_pk_mul_f32 v[90:91], v[90:91], v[100:101] op_sel_hi:[1,0]
	v_pk_mul_f32 v[84:85], v[84:85], v[100:101] op_sel_hi:[1,0]
	v_pk_mul_f32 v[86:87], v[86:87], v[100:101] op_sel_hi:[1,0]
	v_pk_mul_f32 v[80:81], v[80:81], v[100:101] op_sel_hi:[1,0]
	v_pk_mul_f32 v[82:83], v[82:83], v[100:101] op_sel_hi:[1,0]
	v_mul_f32_e32 v97, 0xbfb8aa3b, v92
	v_mul_f32_e32 v100, 0xbfb8aa3b, v93
	v_mul_f32_e32 v101, 0xbfb8aa3b, v94
	v_mul_f32_e32 v104, 0xbfb8aa3b, v95
	v_mul_f32_e32 v105, 0xbfb8aa3b, v88
	v_mul_f32_e32 v106, 0xbfb8aa3b, v89
	v_mul_f32_e32 v107, 0xbfb8aa3b, v90
	v_mul_f32_e32 v108, 0xbfb8aa3b, v91
	v_exp_f32_e32 v97, v97
	v_exp_f32_e32 v100, v100
	v_exp_f32_e32 v101, v101
	v_exp_f32_e32 v104, v104
	v_exp_f32_e32 v105, v105
	v_exp_f32_e32 v106, v106
	v_exp_f32_e32 v107, v107
	v_exp_f32_e32 v108, v108
	v_add_f32_e32 v97, 1.0, v97
	v_add_f32_e32 v109, 1.0, v100
	v_add_f32_e32 v110, 1.0, v101
	v_add_f32_e32 v111, 1.0, v104
	v_add_f32_e32 v112, 1.0, v105
	v_add_f32_e32 v113, 1.0, v106
	v_add_f32_e32 v114, 1.0, v107
	v_add_f32_e32 v115, 1.0, v108
	v_rcp_f32_e32 v100, v97
	v_rcp_f32_e32 v101, v109
	v_rcp_f32_e32 v104, v110
	v_rcp_f32_e32 v105, v111
	v_rcp_f32_e32 v106, v112
	v_rcp_f32_e32 v107, v113
	v_rcp_f32_e32 v108, v114
	v_rcp_f32_e32 v109, v115
	v_pk_mul_f32 v[92:93], v[92:93], v[100:101]
	v_pk_mul_f32 v[94:95], v[94:95], v[104:105]
	v_pk_mul_f32 v[88:89], v[88:89], v[106:107]
	v_pk_mul_f32 v[90:91], v[90:91], v[108:109]
	v_pk_mul_f32 v[84:85], v[84:85], v[92:93]
	v_pk_mul_f32 v[86:87], v[86:87], v[94:95]
	v_pk_mul_f32 v[88:89], v[80:81], v[88:89]
	v_pk_mul_f32 v[90:91], v[82:83], v[90:91]
	v_cvt_pk_bf16_f32 v80, v84, v85
	v_cvt_pk_bf16_f32 v81, v86, v87
	v_cvt_pk_bf16_f32 v82, v88, v89
	v_cvt_pk_bf16_f32 v83, v90, v91
	global_store_dwordx4 v[98:99], v[80:83], off
	s_nop 0
	s_nop 0
	v_mad_i64_i32 v[82:83], s[38:39], v96, s58, v[146:147]
	v_lshl_add_u64 v[82:83], v[82:83], 0, v[148:149]
	v_fmamk_f32 v80, v247, 0x3a800000, v158
	v_rsq_f32_e32 v80, v80
	s_nop 0
	v_pk_mul_f32 v[76:77], v[76:77], v[80:81] op_sel_hi:[1,0]
	v_pk_mul_f32 v[78:79], v[78:79], v[80:81] op_sel_hi:[1,0]
	v_pk_mul_f32 v[72:73], v[72:73], v[80:81] op_sel_hi:[1,0]
	v_pk_mul_f32 v[74:75], v[74:75], v[80:81] op_sel_hi:[1,0]
	v_pk_mul_f32 v[68:69], v[68:69], v[80:81] op_sel_hi:[1,0]
	v_pk_mul_f32 v[70:71], v[70:71], v[80:81] op_sel_hi:[1,0]
	v_pk_mul_f32 v[64:65], v[64:65], v[80:81] op_sel_hi:[1,0]
	v_pk_mul_f32 v[66:67], v[66:67], v[80:81] op_sel_hi:[1,0]
	v_mul_f32_e32 v80, 0xbfb8aa3b, v76
	v_mul_f32_e32 v81, 0xbfb8aa3b, v77
	v_mul_f32_e32 v84, 0xbfb8aa3b, v78
	v_mul_f32_e32 v85, 0xbfb8aa3b, v79
	v_mul_f32_e32 v86, 0xbfb8aa3b, v72
	v_mul_f32_e32 v87, 0xbfb8aa3b, v73
	v_mul_f32_e32 v88, 0xbfb8aa3b, v74
	v_mul_f32_e32 v89, 0xbfb8aa3b, v75
	v_exp_f32_e32 v80, v80
	v_exp_f32_e32 v81, v81
	v_exp_f32_e32 v84, v84
	v_exp_f32_e32 v85, v85
	v_exp_f32_e32 v86, v86
	v_exp_f32_e32 v87, v87
	v_exp_f32_e32 v88, v88
	v_exp_f32_e32 v89, v89
	v_add_f32_e32 v80, 1.0, v80
	v_add_f32_e32 v81, 1.0, v81
	v_add_f32_e32 v84, 1.0, v84
	v_add_f32_e32 v85, 1.0, v85
	v_add_f32_e32 v86, 1.0, v86
	v_add_f32_e32 v87, 1.0, v87
	v_add_f32_e32 v88, 1.0, v88
	v_add_f32_e32 v89, 1.0, v89
	v_rcp_f32_e32 v80, v80
	v_rcp_f32_e32 v81, v81
	v_rcp_f32_e32 v84, v84
	v_rcp_f32_e32 v85, v85
	v_rcp_f32_e32 v86, v86
	v_rcp_f32_e32 v87, v87
	v_rcp_f32_e32 v88, v88
	v_rcp_f32_e32 v89, v89
	v_pk_mul_f32 v[76:77], v[76:77], v[80:81]
	v_pk_mul_f32 v[78:79], v[78:79], v[84:85]
	v_pk_mul_f32 v[72:73], v[72:73], v[86:87]
	v_pk_mul_f32 v[74:75], v[74:75], v[88:89]
	v_pk_mul_f32 v[68:69], v[68:69], v[76:77]
	v_pk_mul_f32 v[70:71], v[70:71], v[78:79]
	v_pk_mul_f32 v[72:73], v[64:65], v[72:73]
	v_pk_mul_f32 v[74:75], v[66:67], v[74:75]
	v_cvt_pk_bf16_f32 v64, v68, v69
	v_cvt_pk_bf16_f32 v65, v70, v71
	v_cvt_pk_bf16_f32 v66, v72, v73
	v_cvt_pk_bf16_f32 v67, v74, v75
	global_store_dwordx4 v[82:83], v[64:67], off
	s_nop 0
	s_nop 0
	v_add_u32_e32 v65, 0x80, v144
	v_mad_i64_i32 v[66:67], s[38:39], v65, s58, v[146:147]
	v_lshl_add_u64 v[66:67], v[66:67], 0, v[148:149]
	v_fmamk_f32 v64, v248, 0x3a800000, v158
	v_rsq_f32_e32 v64, v64
	s_nop 0
	v_pk_mul_f32 v[60:61], v[60:61], v[64:65] op_sel_hi:[1,0]
	v_pk_mul_f32 v[62:63], v[62:63], v[64:65] op_sel_hi:[1,0]
	v_pk_mul_f32 v[56:57], v[56:57], v[64:65] op_sel_hi:[1,0]
	v_pk_mul_f32 v[58:59], v[58:59], v[64:65] op_sel_hi:[1,0]
	v_pk_mul_f32 v[52:53], v[52:53], v[64:65] op_sel_hi:[1,0]
	v_pk_mul_f32 v[54:55], v[54:55], v[64:65] op_sel_hi:[1,0]
	v_pk_mul_f32 v[48:49], v[48:49], v[64:65] op_sel_hi:[1,0]
	v_pk_mul_f32 v[50:51], v[50:51], v[64:65] op_sel_hi:[1,0]
	v_mul_f32_e32 v64, 0xbfb8aa3b, v60
	v_mul_f32_e32 v65, 0xbfb8aa3b, v61
	v_mul_f32_e32 v68, 0xbfb8aa3b, v62
	v_mul_f32_e32 v69, 0xbfb8aa3b, v63
	v_mul_f32_e32 v70, 0xbfb8aa3b, v56
	v_mul_f32_e32 v71, 0xbfb8aa3b, v57
	v_mul_f32_e32 v72, 0xbfb8aa3b, v58
	v_mul_f32_e32 v73, 0xbfb8aa3b, v59
	v_exp_f32_e32 v64, v64
	v_exp_f32_e32 v65, v65
	v_exp_f32_e32 v68, v68
	v_exp_f32_e32 v69, v69
	v_exp_f32_e32 v70, v70
	v_exp_f32_e32 v71, v71
	v_exp_f32_e32 v72, v72
	v_exp_f32_e32 v73, v73
	v_add_f32_e32 v64, 1.0, v64
	v_add_f32_e32 v65, 1.0, v65
	v_add_f32_e32 v68, 1.0, v68
	v_add_f32_e32 v69, 1.0, v69
	v_add_f32_e32 v70, 1.0, v70
	v_add_f32_e32 v71, 1.0, v71
	v_add_f32_e32 v72, 1.0, v72
	v_add_f32_e32 v73, 1.0, v73
	v_rcp_f32_e32 v64, v64
	v_rcp_f32_e32 v65, v65
	v_rcp_f32_e32 v68, v68
	v_rcp_f32_e32 v69, v69
	v_rcp_f32_e32 v70, v70
	v_rcp_f32_e32 v71, v71
	v_rcp_f32_e32 v72, v72
	v_rcp_f32_e32 v73, v73
	v_pk_mul_f32 v[60:61], v[60:61], v[64:65]
	v_pk_mul_f32 v[62:63], v[62:63], v[68:69]
	v_pk_mul_f32 v[56:57], v[56:57], v[70:71]
	v_pk_mul_f32 v[58:59], v[58:59], v[72:73]
	v_pk_mul_f32 v[52:53], v[52:53], v[60:61]
	v_pk_mul_f32 v[54:55], v[54:55], v[62:63]
	v_pk_mul_f32 v[56:57], v[48:49], v[56:57]
	v_pk_mul_f32 v[58:59], v[50:51], v[58:59]
	v_cvt_pk_bf16_f32 v48, v52, v53
	v_cvt_pk_bf16_f32 v49, v54, v55
	v_cvt_pk_bf16_f32 v50, v56, v57
	v_cvt_pk_bf16_f32 v51, v58, v59
	global_store_dwordx4 v[66:67], v[48:51], off
	s_nop 0
	s_nop 0
	v_add_u32_e32 v49, 0x90, v144
	v_mad_i64_i32 v[50:51], s[38:39], v49, s58, v[146:147]
	v_lshl_add_u64 v[50:51], v[50:51], 0, v[148:149]
	v_fmamk_f32 v48, v249, 0x3a800000, v158
	v_rsq_f32_e32 v48, v48
	s_nop 0
	v_pk_mul_f32 v[44:45], v[44:45], v[48:49] op_sel_hi:[1,0]
	v_pk_mul_f32 v[46:47], v[46:47], v[48:49] op_sel_hi:[1,0]
	v_pk_mul_f32 v[40:41], v[40:41], v[48:49] op_sel_hi:[1,0]
	v_pk_mul_f32 v[42:43], v[42:43], v[48:49] op_sel_hi:[1,0]
	v_pk_mul_f32 v[36:37], v[36:37], v[48:49] op_sel_hi:[1,0]
	v_pk_mul_f32 v[38:39], v[38:39], v[48:49] op_sel_hi:[1,0]
	v_pk_mul_f32 v[32:33], v[32:33], v[48:49] op_sel_hi:[1,0]
	v_pk_mul_f32 v[34:35], v[34:35], v[48:49] op_sel_hi:[1,0]
	v_mul_f32_e32 v48, 0xbfb8aa3b, v44
	v_mul_f32_e32 v49, 0xbfb8aa3b, v45
	v_mul_f32_e32 v52, 0xbfb8aa3b, v46
	v_mul_f32_e32 v53, 0xbfb8aa3b, v47
	v_mul_f32_e32 v54, 0xbfb8aa3b, v40
	v_mul_f32_e32 v55, 0xbfb8aa3b, v41
	v_mul_f32_e32 v56, 0xbfb8aa3b, v42
	v_mul_f32_e32 v57, 0xbfb8aa3b, v43
	v_exp_f32_e32 v48, v48
	v_exp_f32_e32 v49, v49
	v_exp_f32_e32 v52, v52
	v_exp_f32_e32 v53, v53
	v_exp_f32_e32 v54, v54
	v_exp_f32_e32 v55, v55
	v_exp_f32_e32 v56, v56
	v_exp_f32_e32 v57, v57
	v_add_f32_e32 v48, 1.0, v48
	v_add_f32_e32 v49, 1.0, v49
	v_add_f32_e32 v52, 1.0, v52
	v_add_f32_e32 v53, 1.0, v53
	v_add_f32_e32 v54, 1.0, v54
	v_add_f32_e32 v55, 1.0, v55
	v_add_f32_e32 v56, 1.0, v56
	v_add_f32_e32 v57, 1.0, v57
	v_rcp_f32_e32 v48, v48
	v_rcp_f32_e32 v49, v49
	v_rcp_f32_e32 v52, v52
	v_rcp_f32_e32 v53, v53
	v_rcp_f32_e32 v54, v54
	v_rcp_f32_e32 v55, v55
	v_rcp_f32_e32 v56, v56
	v_rcp_f32_e32 v57, v57
	v_pk_mul_f32 v[44:45], v[44:45], v[48:49]
	v_pk_mul_f32 v[46:47], v[46:47], v[52:53]
	v_pk_mul_f32 v[40:41], v[40:41], v[54:55]
	v_pk_mul_f32 v[42:43], v[42:43], v[56:57]
	v_pk_mul_f32 v[36:37], v[36:37], v[44:45]
	v_pk_mul_f32 v[38:39], v[38:39], v[46:47]
	v_pk_mul_f32 v[40:41], v[32:33], v[40:41]
	v_pk_mul_f32 v[42:43], v[34:35], v[42:43]
	v_cvt_pk_bf16_f32 v32, v36, v37
	v_cvt_pk_bf16_f32 v33, v38, v39
	v_cvt_pk_bf16_f32 v34, v40, v41
	v_cvt_pk_bf16_f32 v35, v42, v43
	global_store_dwordx4 v[50:51], v[32:35], off
	s_nop 0
	s_nop 0
	v_add_u32_e32 v33, 0xa0, v144
	v_mad_i64_i32 v[34:35], s[38:39], v33, s58, v[146:147]
	v_lshl_add_u64 v[34:35], v[34:35], 0, v[148:149]
	v_fmamk_f32 v32, v250, 0x3a800000, v158
	v_rsq_f32_e32 v32, v32
	s_nop 0
	v_pk_mul_f32 v[28:29], v[28:29], v[32:33] op_sel_hi:[1,0]
	v_pk_mul_f32 v[30:31], v[30:31], v[32:33] op_sel_hi:[1,0]
	v_pk_mul_f32 v[24:25], v[24:25], v[32:33] op_sel_hi:[1,0]
	v_pk_mul_f32 v[26:27], v[26:27], v[32:33] op_sel_hi:[1,0]
	v_pk_mul_f32 v[20:21], v[20:21], v[32:33] op_sel_hi:[1,0]
	v_pk_mul_f32 v[22:23], v[22:23], v[32:33] op_sel_hi:[1,0]
	v_pk_mul_f32 v[16:17], v[16:17], v[32:33] op_sel_hi:[1,0]
	v_pk_mul_f32 v[18:19], v[18:19], v[32:33] op_sel_hi:[1,0]
	v_mul_f32_e32 v32, 0xbfb8aa3b, v28
	v_mul_f32_e32 v33, 0xbfb8aa3b, v29
	v_mul_f32_e32 v36, 0xbfb8aa3b, v30
	v_mul_f32_e32 v37, 0xbfb8aa3b, v31
	v_mul_f32_e32 v38, 0xbfb8aa3b, v24
	v_mul_f32_e32 v39, 0xbfb8aa3b, v25
	v_mul_f32_e32 v40, 0xbfb8aa3b, v26
	v_mul_f32_e32 v41, 0xbfb8aa3b, v27
	v_exp_f32_e32 v32, v32
	v_exp_f32_e32 v33, v33
	v_exp_f32_e32 v36, v36
	v_exp_f32_e32 v37, v37
	v_exp_f32_e32 v38, v38
	v_exp_f32_e32 v39, v39
	v_exp_f32_e32 v40, v40
	v_exp_f32_e32 v41, v41
	v_add_f32_e32 v32, 1.0, v32
	v_add_f32_e32 v33, 1.0, v33
	v_add_f32_e32 v36, 1.0, v36
	v_add_f32_e32 v37, 1.0, v37
	v_add_f32_e32 v38, 1.0, v38
	v_add_f32_e32 v39, 1.0, v39
	v_add_f32_e32 v40, 1.0, v40
	v_add_f32_e32 v41, 1.0, v41
	v_rcp_f32_e32 v32, v32
	v_rcp_f32_e32 v33, v33
	v_rcp_f32_e32 v36, v36
	v_rcp_f32_e32 v37, v37
	v_rcp_f32_e32 v38, v38
	v_rcp_f32_e32 v39, v39
	v_rcp_f32_e32 v40, v40
	v_rcp_f32_e32 v41, v41
	v_pk_mul_f32 v[28:29], v[28:29], v[32:33]
	v_pk_mul_f32 v[30:31], v[30:31], v[36:37]
	v_pk_mul_f32 v[24:25], v[24:25], v[38:39]
	v_pk_mul_f32 v[26:27], v[26:27], v[40:41]
	v_pk_mul_f32 v[20:21], v[20:21], v[28:29]
	v_pk_mul_f32 v[22:23], v[22:23], v[30:31]
	v_pk_mul_f32 v[24:25], v[16:17], v[24:25]
	v_pk_mul_f32 v[26:27], v[18:19], v[26:27]
	v_cvt_pk_bf16_f32 v16, v20, v21
	v_cvt_pk_bf16_f32 v17, v22, v23
	v_cvt_pk_bf16_f32 v18, v24, v25
	v_cvt_pk_bf16_f32 v19, v26, v27
	global_store_dwordx4 v[34:35], v[16:19], off
	s_nop 0
	s_nop 0
	v_add_u32_e32 v17, 0xb0, v144
	v_mad_i64_i32 v[18:19], s[38:39], v17, s58, v[146:147]
	v_lshl_add_u64 v[18:19], v[18:19], 0, v[148:149]
	v_fmamk_f32 v16, v251, 0x3a800000, v158
	v_rsq_f32_e32 v16, v16
	s_nop 0
	v_pk_mul_f32 v[12:13], v[12:13], v[16:17] op_sel_hi:[1,0]
	v_pk_mul_f32 v[14:15], v[14:15], v[16:17] op_sel_hi:[1,0]
	v_pk_mul_f32 v[8:9], v[8:9], v[16:17] op_sel_hi:[1,0]
	v_pk_mul_f32 v[10:11], v[10:11], v[16:17] op_sel_hi:[1,0]
	v_pk_mul_f32 v[4:5], v[4:5], v[16:17] op_sel_hi:[1,0]
	v_pk_mul_f32 v[6:7], v[6:7], v[16:17] op_sel_hi:[1,0]
	v_pk_mul_f32 v[0:1], v[0:1], v[16:17] op_sel_hi:[1,0]
	v_pk_mul_f32 v[2:3], v[2:3], v[16:17] op_sel_hi:[1,0]
	v_mul_f32_e32 v16, 0xbfb8aa3b, v12
	v_mul_f32_e32 v17, 0xbfb8aa3b, v13
	v_mul_f32_e32 v20, 0xbfb8aa3b, v14
	v_mul_f32_e32 v21, 0xbfb8aa3b, v15
	v_mul_f32_e32 v22, 0xbfb8aa3b, v8
	v_mul_f32_e32 v23, 0xbfb8aa3b, v9
	v_mul_f32_e32 v24, 0xbfb8aa3b, v10
	v_mul_f32_e32 v25, 0xbfb8aa3b, v11
	v_exp_f32_e32 v16, v16
	v_exp_f32_e32 v17, v17
	v_exp_f32_e32 v20, v20
	v_exp_f32_e32 v21, v21
	v_exp_f32_e32 v22, v22
	v_exp_f32_e32 v23, v23
	v_exp_f32_e32 v24, v24
	v_exp_f32_e32 v25, v25
	v_add_f32_e32 v16, 1.0, v16
	v_add_f32_e32 v17, 1.0, v17
	v_add_f32_e32 v20, 1.0, v20
	v_add_f32_e32 v21, 1.0, v21
	v_add_f32_e32 v22, 1.0, v22
	v_add_f32_e32 v23, 1.0, v23
	v_add_f32_e32 v24, 1.0, v24
	v_add_f32_e32 v25, 1.0, v25
	v_rcp_f32_e32 v16, v16
	v_rcp_f32_e32 v17, v17
	v_rcp_f32_e32 v20, v20
	v_rcp_f32_e32 v21, v21
	v_rcp_f32_e32 v22, v22
	v_rcp_f32_e32 v23, v23
	v_rcp_f32_e32 v24, v24
	v_rcp_f32_e32 v25, v25
	v_pk_mul_f32 v[12:13], v[12:13], v[16:17]
	v_pk_mul_f32 v[14:15], v[14:15], v[20:21]
	v_pk_mul_f32 v[8:9], v[8:9], v[22:23]
	v_pk_mul_f32 v[10:11], v[10:11], v[24:25]
	v_pk_mul_f32 v[4:5], v[4:5], v[12:13]
	v_pk_mul_f32 v[6:7], v[6:7], v[14:15]
	v_pk_mul_f32 v[8:9], v[0:1], v[8:9]
	v_pk_mul_f32 v[10:11], v[2:3], v[10:11]
	v_cvt_pk_bf16_f32 v0, v4, v5
	v_cvt_pk_bf16_f32 v1, v6, v7
	v_cvt_pk_bf16_f32 v2, v8, v9
	v_cvt_pk_bf16_f32 v3, v10, v11
	global_store_dwordx4 v[18:19], v[0:3], off
	s_cbranch_vccnz .LBB0_540
	s_andn2_b64 vcc, exec, s[8:9]
	s_cbranch_vccnz .LBB0_539
	s_barrier
	s_branch .LBB0_539

.LBB0_630:
	v_lshl_add_u32 v144, s51, 8, v146
	v_lshl_or_b32 v142, s52, 8, v148
	v_ashrrev_i32_e32 v145, 31, v144
	v_ashrrev_i32_e32 v143, 31, v142
	v_lshlrev_b64 v[140:141], 10, v[144:145]
	v_lshl_add_u64 v[140:141], v[140:141], 0, v[142:143]
	v_lshl_add_u64 v[152:153], v[140:141], 1, s[8:9]
	global_load_dwordx2 v[244:245], v[152:153], off
	global_load_dwordx2 v[246:247], v[152:153], off offset:32
	global_load_dwordx2 v[248:249], v[152:153], off offset:256
	global_load_dwordx2 v[250:251], v[152:153], off offset:288
	v_lshl_add_u64 v[156:157], v[140:141], 2, s[24:25]
	s_and_b64 vcc, exec, s[0:1]
	s_mov_b64 s[0:1], -1
	s_waitcnt vmcnt(0)
	v_lshlrev_b32_e32 v158, 16, v244
	v_and_b32_e32 v159, 0xffff0000, v244
	v_lshlrev_b32_e32 v154, 16, v245
	v_and_b32_e32 v155, 0xffff0000, v245
	v_pk_add_f32 v[126:127], v[126:127], v[154:155]
	v_pk_add_f32 v[124:125], v[124:125], v[158:159]
	global_store_dwordx4 v[156:157], v[124:127], off nt
	s_nop 1
	v_lshlrev_b32_e32 v126, 16, v246
	v_and_b32_e32 v127, 0xffff0000, v246
	v_lshlrev_b32_e32 v124, 16, v247
	v_and_b32_e32 v125, 0xffff0000, v247
	v_pk_add_f32 v[122:123], v[122:123], v[124:125]
	v_pk_add_f32 v[120:121], v[120:121], v[126:127]
	global_store_dwordx4 v[156:157], v[120:123], off offset:64 nt
	s_nop 1
	v_lshlrev_b32_e32 v122, 16, v248
	v_and_b32_e32 v123, 0xffff0000, v248
	v_lshlrev_b32_e32 v120, 16, v249
	v_and_b32_e32 v121, 0xffff0000, v249
	v_pk_add_f32 v[118:119], v[118:119], v[120:121]
	v_pk_add_f32 v[116:117], v[116:117], v[122:123]
	global_store_dwordx4 v[156:157], v[116:119], off offset:512 nt
	s_nop 1
	v_lshlrev_b32_e32 v122, 16, v250
	v_or_b32_e32 v118, 16, v144
	v_ashrrev_i32_e32 v119, 31, v118
	v_lshlrev_b64 v[118:119], 10, v[118:119]
	v_and_b32_e32 v123, 0xffff0000, v250
	v_lshlrev_b32_e32 v116, 16, v251
	v_and_b32_e32 v117, 0xffff0000, v251
	v_lshl_add_u64 v[118:119], v[118:119], 0, v[142:143]
	v_pk_add_f32 v[110:111], v[110:111], v[116:117]
	v_pk_add_f32 v[108:109], v[108:109], v[122:123]
	v_lshl_add_u64 v[120:121], v[118:119], 1, s[8:9]
	global_store_dwordx4 v[156:157], v[108:111], off offset:576 nt
	global_load_dwordx2 v[244:245], v[120:121], off
	global_load_dwordx2 v[246:247], v[120:121], off offset:32
	global_load_dwordx2 v[248:249], v[120:121], off offset:256
	global_load_dwordx2 v[250:251], v[120:121], off offset:288
	v_lshl_add_u64 v[116:117], v[118:119], 2, s[24:25]
	s_waitcnt vmcnt(0)
	v_lshlrev_b32_e32 v118, 16, v244
	v_and_b32_e32 v119, 0xffff0000, v244
	v_lshlrev_b32_e32 v108, 16, v245
	v_and_b32_e32 v109, 0xffff0000, v245
	v_pk_add_f32 v[110:111], v[114:115], v[108:109]
	v_pk_add_f32 v[108:109], v[112:113], v[118:119]
	global_store_dwordx4 v[116:117], v[108:111], off nt
	s_nop 1
	v_lshlrev_b32_e32 v110, 16, v246
	v_and_b32_e32 v111, 0xffff0000, v246
	v_lshlrev_b32_e32 v108, 16, v247
	v_and_b32_e32 v109, 0xffff0000, v247
	v_pk_add_f32 v[106:107], v[106:107], v[108:109]
	v_pk_add_f32 v[104:105], v[104:105], v[110:111]
	global_store_dwordx4 v[116:117], v[104:107], off offset:64 nt
	s_nop 1
	v_lshlrev_b32_e32 v106, 16, v248
	v_and_b32_e32 v107, 0xffff0000, v248
	v_lshlrev_b32_e32 v104, 16, v249
	v_and_b32_e32 v105, 0xffff0000, v249
	v_pk_add_f32 v[102:103], v[102:103], v[104:105]
	v_pk_add_f32 v[100:101], v[100:101], v[106:107]
	global_store_dwordx4 v[116:117], v[100:103], off offset:512 nt
	s_nop 1
	v_lshlrev_b32_e32 v106, 16, v250
	v_or_b32_e32 v102, 32, v144
	v_ashrrev_i32_e32 v103, 31, v102
	v_lshlrev_b64 v[102:103], 10, v[102:103]
	v_and_b32_e32 v107, 0xffff0000, v250
	v_lshlrev_b32_e32 v100, 16, v251
	v_and_b32_e32 v101, 0xffff0000, v251
	v_lshl_add_u64 v[102:103], v[102:103], 0, v[142:143]
	v_pk_add_f32 v[94:95], v[94:95], v[100:101]
	v_pk_add_f32 v[92:93], v[92:93], v[106:107]
	v_lshl_add_u64 v[104:105], v[102:103], 1, s[8:9]
	global_store_dwordx4 v[116:117], v[92:95], off offset:576 nt
	global_load_dwordx2 v[244:245], v[104:105], off
	global_load_dwordx2 v[246:247], v[104:105], off offset:32
	global_load_dwordx2 v[248:249], v[104:105], off offset:256
	global_load_dwordx2 v[250:251], v[104:105], off offset:288
	v_lshl_add_u64 v[100:101], v[102:103], 2, s[24:25]
	s_waitcnt vmcnt(0)
	v_lshlrev_b32_e32 v102, 16, v244
	v_and_b32_e32 v103, 0xffff0000, v244
	v_lshlrev_b32_e32 v92, 16, v245
	v_and_b32_e32 v93, 0xffff0000, v245
	v_pk_add_f32 v[94:95], v[98:99], v[92:93]
	v_pk_add_f32 v[92:93], v[96:97], v[102:103]
	global_store_dwordx4 v[100:101], v[92:95], off nt
	s_nop 1
	v_lshlrev_b32_e32 v94, 16, v246
	v_and_b32_e32 v95, 0xffff0000, v246
	v_lshlrev_b32_e32 v92, 16, v247
	v_and_b32_e32 v93, 0xffff0000, v247
	v_pk_add_f32 v[90:91], v[90:91], v[92:93]
	v_pk_add_f32 v[88:89], v[88:89], v[94:95]
	global_store_dwordx4 v[100:101], v[88:91], off offset:64 nt
	s_nop 1
	v_lshlrev_b32_e32 v90, 16, v248
	v_and_b32_e32 v91, 0xffff0000, v248
	v_lshlrev_b32_e32 v88, 16, v249
	v_and_b32_e32 v89, 0xffff0000, v249
	v_pk_add_f32 v[86:87], v[86:87], v[88:89]
	v_pk_add_f32 v[84:85], v[84:85], v[90:91]
	global_store_dwordx4 v[100:101], v[84:87], off offset:512 nt
	s_nop 1
	v_lshlrev_b32_e32 v90, 16, v250
	v_or_b32_e32 v86, 48, v144
	v_ashrrev_i32_e32 v87, 31, v86
	v_lshlrev_b64 v[86:87], 10, v[86:87]
	v_and_b32_e32 v91, 0xffff0000, v250
	v_lshlrev_b32_e32 v84, 16, v251
	v_and_b32_e32 v85, 0xffff0000, v251
	v_lshl_add_u64 v[86:87], v[86:87], 0, v[142:143]
	v_pk_add_f32 v[78:79], v[78:79], v[84:85]
	v_pk_add_f32 v[76:77], v[76:77], v[90:91]
	v_lshl_add_u64 v[88:89], v[86:87], 1, s[8:9]
	global_store_dwordx4 v[100:101], v[76:79], off offset:576 nt
	global_load_dwordx2 v[244:245], v[88:89], off
	global_load_dwordx2 v[246:247], v[88:89], off offset:32
	global_load_dwordx2 v[248:249], v[88:89], off offset:256
	global_load_dwordx2 v[250:251], v[88:89], off offset:288
	v_lshl_add_u64 v[84:85], v[86:87], 2, s[24:25]
	s_waitcnt vmcnt(0)
	v_lshlrev_b32_e32 v86, 16, v244
	v_and_b32_e32 v87, 0xffff0000, v244
	v_lshlrev_b32_e32 v76, 16, v245
	v_and_b32_e32 v77, 0xffff0000, v245
	v_pk_add_f32 v[78:79], v[82:83], v[76:77]
	v_pk_add_f32 v[76:77], v[80:81], v[86:87]
	global_store_dwordx4 v[84:85], v[76:79], off nt
	s_nop 1
	v_lshlrev_b32_e32 v78, 16, v246
	v_and_b32_e32 v79, 0xffff0000, v246
	v_lshlrev_b32_e32 v76, 16, v247
	v_and_b32_e32 v77, 0xffff0000, v247
	v_pk_add_f32 v[74:75], v[74:75], v[76:77]
	v_pk_add_f32 v[72:73], v[72:73], v[78:79]
	global_store_dwordx4 v[84:85], v[72:75], off offset:64 nt
	s_nop 1
	v_lshlrev_b32_e32 v74, 16, v248
	v_and_b32_e32 v75, 0xffff0000, v248
	v_lshlrev_b32_e32 v72, 16, v249
	v_and_b32_e32 v73, 0xffff0000, v249
	v_pk_add_f32 v[70:71], v[70:71], v[72:73]
	v_pk_add_f32 v[68:69], v[68:69], v[74:75]
	global_store_dwordx4 v[84:85], v[68:71], off offset:512 nt
	s_nop 1
	v_lshlrev_b32_e32 v74, 16, v250
	v_and_b32_e32 v75, 0xffff0000, v250
	v_lshlrev_b32_e32 v68, 16, v251
	v_and_b32_e32 v69, 0xffff0000, v251
	v_lshl_add_u64 v[70:71], v[140:141], 0, s[16:17]
	v_pk_add_f32 v[66:67], v[66:67], v[68:69]
	v_pk_add_f32 v[64:65], v[64:65], v[74:75]
	v_lshl_add_u64 v[72:73], v[70:71], 1, s[8:9]
	global_store_dwordx4 v[84:85], v[64:67], off offset:576 nt
	global_load_dwordx2 v[244:245], v[72:73], off
	global_load_dwordx2 v[246:247], v[72:73], off offset:32
	global_load_dwordx2 v[248:249], v[72:73], off offset:256
	global_load_dwordx2 v[250:251], v[72:73], off offset:288
	s_waitcnt vmcnt(0)
	v_lshlrev_b32_e32 v68, 16, v244
	v_and_b32_e32 v69, 0xffff0000, v244
	v_lshlrev_b32_e32 v64, 16, v245
	v_and_b32_e32 v65, 0xffff0000, v245
	v_lshl_add_u64 v[66:67], v[70:71], 2, s[24:25]
	v_pk_add_f32 v[62:63], v[62:63], v[64:65]
	v_pk_add_f32 v[60:61], v[60:61], v[68:69]
	global_store_dwordx4 v[66:67], v[60:63], off nt
	s_nop 1
	v_lshlrev_b32_e32 v62, 16, v246
	v_and_b32_e32 v63, 0xffff0000, v246
	v_lshlrev_b32_e32 v60, 16, v247
	v_and_b32_e32 v61, 0xffff0000, v247
	v_pk_add_f32 v[58:59], v[58:59], v[60:61]
	v_pk_add_f32 v[56:57], v[56:57], v[62:63]
	global_store_dwordx4 v[66:67], v[56:59], off offset:64 nt
	s_nop 1
	v_lshlrev_b32_e32 v58, 16, v248
	v_and_b32_e32 v59, 0xffff0000, v248
	v_lshlrev_b32_e32 v56, 16, v249
	v_and_b32_e32 v57, 0xffff0000, v249
	v_pk_add_f32 v[54:55], v[54:55], v[56:57]
	v_pk_add_f32 v[52:53], v[52:53], v[58:59]
	global_store_dwordx4 v[66:67], v[52:55], off offset:512 nt
	s_nop 1
	v_lshlrev_b32_e32 v58, 16, v250
	v_and_b32_e32 v59, 0xffff0000, v250
	v_lshlrev_b32_e32 v52, 16, v251
	v_and_b32_e32 v53, 0xffff0000, v251
	v_lshl_add_u64 v[54:55], v[140:141], 0, s[18:19]
	v_pk_add_f32 v[46:47], v[46:47], v[52:53]
	v_pk_add_f32 v[44:45], v[44:45], v[58:59]
	v_lshl_add_u64 v[56:57], v[54:55], 1, s[8:9]
	global_store_dwordx4 v[66:67], v[44:47], off offset:576 nt
	global_load_dwordx2 v[244:245], v[56:57], off
	global_load_dwordx2 v[246:247], v[56:57], off offset:32
	global_load_dwordx2 v[248:249], v[56:57], off offset:256
	global_load_dwordx2 v[250:251], v[56:57], off offset:288
	v_lshl_add_u64 v[52:53], v[54:55], 2, s[24:25]
	s_waitcnt vmcnt(0)
	v_lshlrev_b32_e32 v54, 16, v244
	v_and_b32_e32 v55, 0xffff0000, v244
	v_lshlrev_b32_e32 v44, 16, v245
	v_and_b32_e32 v45, 0xffff0000, v245
	v_pk_add_f32 v[46:47], v[50:51], v[44:45]
	v_pk_add_f32 v[44:45], v[48:49], v[54:55]
	global_store_dwordx4 v[52:53], v[44:47], off nt
	s_nop 1
	v_lshlrev_b32_e32 v46, 16, v246
	v_and_b32_e32 v47, 0xffff0000, v246
	v_lshlrev_b32_e32 v44, 16, v247
	v_and_b32_e32 v45, 0xffff0000, v247
	v_pk_add_f32 v[42:43], v[42:43], v[44:45]
	v_pk_add_f32 v[40:41], v[40:41], v[46:47]
	global_store_dwordx4 v[52:53], v[40:43], off offset:64 nt
	s_nop 1
	v_lshlrev_b32_e32 v42, 16, v248
	v_and_b32_e32 v43, 0xffff0000, v248
	v_lshlrev_b32_e32 v40, 16, v249
	v_and_b32_e32 v41, 0xffff0000, v249
	v_pk_add_f32 v[38:39], v[38:39], v[40:41]
	v_pk_add_f32 v[36:37], v[36:37], v[42:43]
	global_store_dwordx4 v[52:53], v[36:39], off offset:512 nt
	s_nop 1
	v_lshlrev_b32_e32 v42, 16, v250
	v_and_b32_e32 v43, 0xffff0000, v250
	v_lshlrev_b32_e32 v36, 16, v251
	v_and_b32_e32 v37, 0xffff0000, v251
	v_lshl_add_u64 v[38:39], v[140:141], 0, s[20:21]
	v_pk_add_f32 v[30:31], v[30:31], v[36:37]
	v_pk_add_f32 v[28:29], v[28:29], v[42:43]
	v_lshl_add_u64 v[40:41], v[38:39], 1, s[8:9]
	global_store_dwordx4 v[52:53], v[28:31], off offset:576 nt
	global_load_dwordx2 v[244:245], v[40:41], off
	global_load_dwordx2 v[246:247], v[40:41], off offset:32
	global_load_dwordx2 v[248:249], v[40:41], off offset:256
	global_load_dwordx2 v[250:251], v[40:41], off offset:288
	v_lshl_add_u64 v[36:37], v[38:39], 2, s[24:25]
	s_waitcnt vmcnt(0)
	v_lshlrev_b32_e32 v38, 16, v244
	v_and_b32_e32 v39, 0xffff0000, v244
	v_lshlrev_b32_e32 v28, 16, v245
	v_and_b32_e32 v29, 0xffff0000, v245
	v_pk_add_f32 v[30:31], v[34:35], v[28:29]
	v_pk_add_f32 v[28:29], v[32:33], v[38:39]
	global_store_dwordx4 v[36:37], v[28:31], off nt
	s_nop 1
	v_lshlrev_b32_e32 v30, 16, v246
	v_and_b32_e32 v31, 0xffff0000, v246
	v_lshlrev_b32_e32 v28, 16, v247
	v_and_b32_e32 v29, 0xffff0000, v247
	v_pk_add_f32 v[26:27], v[26:27], v[28:29]
	v_pk_add_f32 v[24:25], v[24:25], v[30:31]
	global_store_dwordx4 v[36:37], v[24:27], off offset:64 nt
	s_nop 1
	v_lshlrev_b32_e32 v26, 16, v248
	v_and_b32_e32 v27, 0xffff0000, v248
	v_lshlrev_b32_e32 v24, 16, v249
	v_and_b32_e32 v25, 0xffff0000, v249
	v_pk_add_f32 v[22:23], v[22:23], v[24:25]
	v_pk_add_f32 v[20:21], v[20:21], v[26:27]
	global_store_dwordx4 v[36:37], v[20:23], off offset:512 nt
	s_nop 1
	v_lshlrev_b32_e32 v26, 16, v250
	v_and_b32_e32 v27, 0xffff0000, v250
	v_lshlrev_b32_e32 v20, 16, v251
	v_and_b32_e32 v21, 0xffff0000, v251
	v_lshl_add_u64 v[22:23], v[140:141], 0, s[22:23]
	v_pk_add_f32 v[14:15], v[14:15], v[20:21]
	v_pk_add_f32 v[12:13], v[12:13], v[26:27]
	v_lshl_add_u64 v[24:25], v[22:23], 1, s[8:9]
	global_store_dwordx4 v[36:37], v[12:15], off offset:576 nt
	global_load_dwordx2 v[244:245], v[24:25], off
	global_load_dwordx2 v[246:247], v[24:25], off offset:32
	global_load_dwordx2 v[248:249], v[24:25], off offset:256
	global_load_dwordx2 v[250:251], v[24:25], off offset:288
	v_lshl_add_u64 v[20:21], v[22:23], 2, s[24:25]
	s_waitcnt vmcnt(0)
	v_lshlrev_b32_e32 v22, 16, v244
	v_and_b32_e32 v23, 0xffff0000, v244
	v_lshlrev_b32_e32 v12, 16, v245
	v_and_b32_e32 v13, 0xffff0000, v245
	v_pk_add_f32 v[14:15], v[18:19], v[12:13]
	v_pk_add_f32 v[12:13], v[16:17], v[22:23]
	global_store_dwordx4 v[20:21], v[12:15], off nt
	s_nop 1
	v_lshlrev_b32_e32 v14, 16, v246
	v_and_b32_e32 v15, 0xffff0000, v246
	v_lshlrev_b32_e32 v12, 16, v247
	v_and_b32_e32 v13, 0xffff0000, v247
	v_pk_add_f32 v[10:11], v[10:11], v[12:13]
	v_pk_add_f32 v[8:9], v[8:9], v[14:15]
	global_store_dwordx4 v[20:21], v[8:11], off offset:64 nt
	s_nop 1
	v_lshlrev_b32_e32 v10, 16, v248
	v_and_b32_e32 v11, 0xffff0000, v248
	v_lshlrev_b32_e32 v8, 16, v249
	v_and_b32_e32 v9, 0xffff0000, v249
	v_pk_add_f32 v[6:7], v[6:7], v[8:9]
	v_pk_add_f32 v[4:5], v[4:5], v[10:11]
	global_store_dwordx4 v[20:21], v[4:7], off offset:512 nt
	s_nop 1
	v_lshlrev_b32_e32 v6, 16, v250
	v_and_b32_e32 v7, 0xffff0000, v250
	v_lshlrev_b32_e32 v4, 16, v251
	v_and_b32_e32 v5, 0xffff0000, v251
	v_pk_add_f32 v[2:3], v[2:3], v[4:5]
	v_pk_add_f32 v[0:1], v[0:1], v[6:7]
	global_store_dwordx4 v[20:21], v[0:3], off offset:576 nt
	s_cbranch_vccnz .LBB0_615
	s_andn2_b64 vcc, exec, s[6:7]
	s_cbranch_vccnz .LBB0_614
	s_barrier
	s_branch .LBB0_614

	.amdhsa_kernel _Z10fwd_kernel4Args
		.amdhsa_group_segment_fixed_size 0
		.amdhsa_private_segment_fixed_size 0
		.amdhsa_kernarg_size 424
		.amdhsa_user_sgpr_count 2
		.amdhsa_user_sgpr_dispatch_ptr 0
		.amdhsa_user_sgpr_queue_ptr 0
		.amdhsa_user_sgpr_kernarg_segment_ptr 1
		.amdhsa_user_sgpr_dispatch_id 0
		.amdhsa_user_sgpr_kernarg_preload_length 0
		.amdhsa_user_sgpr_kernarg_preload_offset 0
		.amdhsa_user_sgpr_private_segment_size 0
		.amdhsa_uses_dynamic_stack 0
		.amdhsa_enable_private_segment 0
		.amdhsa_system_sgpr_workgroup_id_x 1
		.amdhsa_system_sgpr_workgroup_id_y 0
		.amdhsa_system_sgpr_workgroup_id_z 0
		.amdhsa_system_sgpr_workgroup_info 0
		.amdhsa_system_vgpr_workitem_id 2
		.amdhsa_next_free_vgpr 252
		.amdhsa_next_free_sgpr 101
		.amdhsa_accum_offset 252
		.amdhsa_reserve_vcc 1
		.amdhsa_float_round_mode_32 0
		.amdhsa_float_round_mode_16_64 0
		.amdhsa_float_denorm_mode_32 3
		.amdhsa_float_denorm_mode_16_64 3
		.amdhsa_dx10_clamp 1
		.amdhsa_ieee_mode 1
		.amdhsa_fp16_overflow 0
		.amdhsa_tg_split 0
		.amdhsa_exception_fp_ieee_invalid_op 0
		.amdhsa_exception_fp_denorm_src 0
		.amdhsa_exception_fp_ieee_div_zero 0
		.amdhsa_exception_fp_ieee_overflow 0
		.amdhsa_exception_fp_ieee_underflow 0
		.amdhsa_exception_fp_ieee_inexact 0
		.amdhsa_exception_int_div_zero 0
	.end_amdhsa_kernel

amdhsa.kernels:
  - .agpr_count:     0
    .args:
      - .offset:         0
        .size:           168
        .value_kind:     by_value
      - .offset:         168
        .size:           4
        .value_kind:     hidden_block_count_x
      - .offset:         172
        .size:           4
        .value_kind:     hidden_block_count_y
      - .offset:         176
        .size:           4
        .value_kind:     hidden_block_count_z
      - .offset:         180
        .size:           2
        .value_kind:     hidden_group_size_x
      - .offset:         182
        .size:           2
        .value_kind:     hidden_group_size_y
      - .offset:         184
        .size:           2
        .value_kind:     hidden_group_size_z
      - .offset:         186
        .size:           2
        .value_kind:     hidden_remainder_x
      - .offset:         188
        .size:           2
        .value_kind:     hidden_remainder_y
      - .offset:         190
        .size:           2
        .value_kind:     hidden_remainder_z
      - .offset:         208
        .size:           8
        .value_kind:     hidden_global_offset_x
      - .offset:         216
        .size:           8
        .value_kind:     hidden_global_offset_y
      - .offset:         224
        .size:           8
        .value_kind:     hidden_global_offset_z
      - .offset:         232
        .size:           2
        .value_kind:     hidden_grid_dims
      - .offset:         256
        .size:           8
        .value_kind:     hidden_multigrid_sync_arg
      - .offset:         288
        .size:           4
        .value_kind:     hidden_dynamic_lds_size
    .group_segment_fixed_size: 0
    .kernarg_segment_align: 8
    .kernarg_segment_size: 424
    .language:       OpenCL C
    .language_version:
      - 2
      - 0
    .max_flat_workgroup_size: 512
    .name:           _Z10fwd_kernel4Args
    .private_segment_fixed_size: 0
    .sgpr_count:     107
    .sgpr_spill_count: 52
    .symbol:         _Z10fwd_kernel4Args.kd
    .uniform_work_group_size: 1
    .uses_dynamic_stack: false
    .vgpr_count:     252
    .vgpr_spill_count: 0
    .wavefront_size: 64
